# setprio reorder + adaLN GEMV phase: 16 row loads kept in flight per wave (rolling refill behind vmcnt(15)), first batch issued ahead of the silu prologue
# speedup vs baseline: 1.0079x; 1.0079x over previous
.LBB8_12:
	s_mul_hi_i32 s0, s29, 0x2aaaaaab
	s_lshr_b32 s1, s0, 31
	s_ashr_i32 s0, s0, 4
	s_add_i32 s0, s0, s1
	s_lshl_b32 s1, s0, 9
	v_or_b32_e32 v2, s1, v0
	v_ashrrev_i32_e32 v3, 31, v2
	v_lshl_add_u64 v[2:3], v[2:3], 2, s[54:55]
	v_add_co_u32_e32 v4, vcc, 0x4000, v2
	s_mulk_i32 s0, 0x60
	s_nop 0
	v_addc_co_u32_e32 v5, vcc, 0, v3, vcc
	v_add_co_u32_e32 v6, vcc, s8, v2
	s_sub_i32 s0, s29, s0
	s_nop 0
	v_addc_co_u32_e32 v7, vcc, 0, v3, vcc
	global_load_dword v14, v[2:3], off
	global_load_dword v15, v[4:5], off
	global_load_dword v16, v[6:7], off
	v_add_co_u32_e32 v2, vcc, s9, v2
	s_lshl_b32 s0, s0, 8
	s_nop 0
	v_addc_co_u32_e32 v3, vcc, 0, v3, vcc
	global_load_dword v17, v[2:3], off
	v_or_b32_e32 v18, s0, v67
	v_ashrrev_i32_e32 v19, 31, v18
	v_or_b32_e32 v24, s1, v68
	v_lshlrev_b64 v[18:19], 2, v[18:19]
	v_mad_i64_i32 v[18:19], s[70:71], v24, s10, v[18:19]
	s_mov_b64 s[4:5], 0
	v_mov_b32_e32 v54, v74
	v_mov_b32_e32 v10, v55
	v_mov_b32_e32 v11, v55
	v_mov_b32_e32 v12, v55
	v_mov_b32_e32 v13, v55
	v_mov_b32_e32 v6, v55
	v_mov_b32_e32 v7, v55
	v_mov_b32_e32 v8, v55
	v_mov_b32_e32 v9, v55
	v_mov_b32_e32 v2, v55
	v_mov_b32_e32 v3, v55
	v_mov_b32_e32 v4, v55
	v_mov_b32_e32 v5, v55
	v_mov_b32_e32 v60, v55
	v_mov_b32_e32 v61, v55
	v_mov_b32_e32 v62, v55
	v_lshl_add_u64 v[58:59], s[56:57], 0, v[18:19]
	v_lshl_add_u64 v[64:65], v[58:59], 0, s[4:5]
	v_add_co_u32_e32 v106, vcc, s10, v64
	s_nop 1
	v_addc_co_u32_e32 v107, vcc, 0, v65, vcc
	v_add_co_u32_e32 v110, vcc, s11, v64
	s_nop 1
	global_load_dwordx4 v[102:105], v[64:65], off
	s_nop 0
	v_addc_co_u32_e32 v111, vcc, 0, v65, vcc
	v_add_co_u32_e32 v114, vcc, s12, v64
	s_nop 1
	v_addc_co_u32_e32 v115, vcc, 0, v65, vcc
	v_add_co_u32_e32 v118, vcc, s13, v64
	s_nop 1
	v_addc_co_u32_e32 v119, vcc, 0, v65, vcc
	v_add_co_u32_e32 v122, vcc, s14, v64
	s_nop 1
	v_addc_co_u32_e32 v123, vcc, 0, v65, vcc
	v_add_co_u32_e32 v126, vcc, s15, v64
	s_nop 1
	v_addc_co_u32_e32 v127, vcc, 0, v65, vcc
	v_add_co_u32_e32 v130, vcc, s16, v64
	s_nop 1
	v_addc_co_u32_e32 v131, vcc, 0, v65, vcc
	v_add_co_u32_e32 v134, vcc, s17, v64
	s_nop 1
	v_addc_co_u32_e32 v135, vcc, 0, v65, vcc
	v_add_co_u32_e32 v138, vcc, s20, v64
	s_nop 1
	v_addc_co_u32_e32 v139, vcc, 0, v65, vcc
	v_add_co_u32_e32 v142, vcc, s21, v64
	s_nop 1
	v_addc_co_u32_e32 v143, vcc, 0, v65, vcc
	v_add_co_u32_e32 v146, vcc, s22, v64
	s_nop 1
	v_addc_co_u32_e32 v147, vcc, 0, v65, vcc
	v_add_co_u32_e32 v150, vcc, s23, v64
	s_nop 1
	v_addc_co_u32_e32 v151, vcc, 0, v65, vcc
	v_add_co_u32_e32 v154, vcc, s24, v64
	s_nop 1
	v_addc_co_u32_e32 v155, vcc, 0, v65, vcc
	v_add_co_u32_e32 v158, vcc, s25, v64
	s_nop 1
	v_addc_co_u32_e32 v159, vcc, 0, v65, vcc
	v_add_co_u32_e32 v64, vcc, s28, v64
	s_nop 1
	v_addc_co_u32_e32 v65, vcc, 0, v65, vcc
	global_load_dwordx4 v[106:109], v[106:107], off
	s_nop 0
	global_load_dwordx4 v[110:113], v[110:111], off
	s_nop 0
	global_load_dwordx4 v[114:117], v[114:115], off
	s_nop 0
	global_load_dwordx4 v[118:121], v[118:119], off
	s_nop 0
	global_load_dwordx4 v[122:125], v[122:123], off
	s_nop 0
	global_load_dwordx4 v[126:129], v[126:127], off
	s_nop 0
	global_load_dwordx4 v[130:133], v[130:131], off
	s_nop 0
	global_load_dwordx4 v[134:137], v[134:135], off
	s_nop 0
	global_load_dwordx4 v[138:141], v[138:139], off
	s_nop 0
	global_load_dwordx4 v[142:145], v[142:143], off
	s_nop 0
	global_load_dwordx4 v[146:149], v[146:147], off
	s_nop 0
	global_load_dwordx4 v[150:153], v[150:151], off
	s_nop 0
	global_load_dwordx4 v[154:157], v[154:155], off
	s_nop 0
	global_load_dwordx4 v[158:161], v[158:159], off
	s_nop 0
	global_load_dwordx4 v[162:165], v[64:65], off
	v_mov_b32_e32 v63, v55
	s_waitcnt vmcnt(19)
	v_mul_f32_e32 v20, 0xbfb8aa3b, v14
	s_waitcnt vmcnt(18)
	v_mul_f32_e32 v21, 0xbfb8aa3b, v15
	s_waitcnt vmcnt(17)
	v_mul_f32_e32 v22, 0xbfb8aa3b, v16
	v_exp_f32_e32 v20, v20
	v_exp_f32_e32 v21, v21
	v_exp_f32_e32 v22, v22
	v_add_f32_e32 v20, 1.0, v20
	s_waitcnt vmcnt(16)
	v_mul_f32_e32 v23, 0xbfb8aa3b, v17
	v_exp_f32_e32 v23, v23
	v_add_f32_e32 v21, 1.0, v21
	v_add_f32_e32 v22, 1.0, v22
	v_rcp_f32_e32 v20, v20
	v_add_f32_e32 v23, 1.0, v23
	v_rcp_f32_e32 v21, v21
	v_rcp_f32_e32 v22, v22
	v_rcp_f32_e32 v23, v23
	v_pk_mul_f32 v[14:15], v[14:15], v[20:21]
	v_pk_mul_f32 v[16:17], v[16:17], v[22:23]
	ds_write_b128 v66, v[14:17] offset:32768
	s_waitcnt lgkmcnt(0)
	s_barrier
.LBB8_13:
.Lq_p0_loop:
	s_add_u32 s4, s4, 0x180000
	s_addc_u32 s5, s5, 0
	v_lshl_add_u64 v[196:197], v[58:59], 0, s[4:5]
	ds_read_b128 v[26:29], v54
	ds_read_b128 v[22:25], v54 offset:16
	ds_read_b128 v[18:21], v54 offset:32
	ds_read_b128 v[14:17], v54 offset:48
	ds_read_b128 v[30:33], v54 offset:64
	ds_read_b128 v[34:37], v54 offset:80
	ds_read_b128 v[38:41], v54 offset:96
	ds_read_b128 v[42:45], v54 offset:112
	ds_read_b128 v[46:49], v54 offset:128
	ds_read_b128 v[50:53], v54 offset:144
	ds_read_b128 v[78:81], v54 offset:160
	ds_read_b128 v[82:85], v54 offset:176
	ds_read_b128 v[86:89], v54 offset:192
	ds_read_b128 v[90:93], v54 offset:208
	ds_read_b128 v[94:97], v54 offset:224
	ds_read_b128 v[98:101], v54 offset:240
	s_waitcnt lgkmcnt(0)
	v_mov_b32_e32 v166, v25
	v_mov_b32_e32 v168, v21
	v_mov_b32_e32 v170, v17
	v_mov_b32_e32 v172, v33
	v_mov_b32_e32 v174, v37
	v_mov_b32_e32 v176, v41
	v_mov_b32_e32 v178, v45
	v_mov_b32_e32 v180, v49
	v_mov_b32_e32 v182, v53
	v_mov_b32_e32 v184, v81
	v_mov_b32_e32 v186, v85
	v_mov_b32_e32 v188, v89
	v_mov_b32_e32 v190, v93
	v_mov_b32_e32 v64, v29
	v_mov_b32_e32 v192, v97
	v_mov_b32_e32 v194, v101
	v_add_u32_e32 v54, 0x100, v54
	s_waitcnt vmcnt(15)
	v_pk_fma_f32 v[10:11], v[102:103], v[26:27], v[10:11] op_sel_hi:[1,0,1]
	v_pk_fma_f32 v[12:13], v[104:105], v[26:27], v[12:13] op_sel_hi:[1,0,1]
	v_pk_fma_f32 v[6:7], v[102:103], v[26:27], v[6:7] op_sel:[0,1,0]
	v_pk_fma_f32 v[8:9], v[104:105], v[26:27], v[8:9] op_sel:[0,1,0]
	v_pk_fma_f32 v[2:3], v[102:103], v[28:29], v[2:3] op_sel_hi:[1,0,1]
	v_pk_fma_f32 v[4:5], v[104:105], v[28:29], v[4:5] op_sel_hi:[1,0,1]
	v_pk_fma_f32 v[26:27], v[102:103], v[64:65], v[62:63] op_sel_hi:[1,0,1]
	v_pk_fma_f32 v[28:29], v[104:105], v[64:65], v[60:61] op_sel_hi:[1,0,1]
	global_load_dwordx4 v[102:105], v[196:197], off
	v_add_co_u32_e32 v198, vcc, s10, v196
	s_waitcnt vmcnt(15)
	v_pk_fma_f32 v[10:11], v[106:107], v[22:23], v[10:11] op_sel_hi:[1,0,1]
	v_pk_fma_f32 v[12:13], v[108:109], v[22:23], v[12:13] op_sel_hi:[1,0,1]
	v_pk_fma_f32 v[6:7], v[106:107], v[22:23], v[6:7] op_sel:[0,1,0]
	v_pk_fma_f32 v[8:9], v[108:109], v[22:23], v[8:9] op_sel:[0,1,0]
	v_pk_fma_f32 v[2:3], v[106:107], v[24:25], v[2:3] op_sel_hi:[1,0,1]
	v_pk_fma_f32 v[4:5], v[108:109], v[24:25], v[4:5] op_sel_hi:[1,0,1]
	v_pk_fma_f32 v[22:23], v[106:107], v[166:167], v[26:27] op_sel_hi:[1,0,1]
	v_pk_fma_f32 v[24:25], v[108:109], v[166:167], v[28:29] op_sel_hi:[1,0,1]
	v_addc_co_u32_e32 v199, vcc, 0, v197, vcc
	global_load_dwordx4 v[106:109], v[198:199], off
	v_add_co_u32_e32 v198, vcc, s11, v196
	s_waitcnt vmcnt(15)
	v_pk_fma_f32 v[10:11], v[110:111], v[18:19], v[10:11] op_sel_hi:[1,0,1]
	v_pk_fma_f32 v[12:13], v[112:113], v[18:19], v[12:13] op_sel_hi:[1,0,1]
	v_pk_fma_f32 v[6:7], v[110:111], v[18:19], v[6:7] op_sel:[0,1,0]
	v_pk_fma_f32 v[8:9], v[112:113], v[18:19], v[8:9] op_sel:[0,1,0]
	v_pk_fma_f32 v[2:3], v[110:111], v[20:21], v[2:3] op_sel_hi:[1,0,1]
	v_pk_fma_f32 v[4:5], v[112:113], v[20:21], v[4:5] op_sel_hi:[1,0,1]
	v_pk_fma_f32 v[18:19], v[110:111], v[168:169], v[22:23] op_sel_hi:[1,0,1]
	v_pk_fma_f32 v[20:21], v[112:113], v[168:169], v[24:25] op_sel_hi:[1,0,1]
	v_addc_co_u32_e32 v199, vcc, 0, v197, vcc
	global_load_dwordx4 v[110:113], v[198:199], off
	v_add_co_u32_e32 v198, vcc, s12, v196
	s_waitcnt vmcnt(15)
	v_pk_fma_f32 v[10:11], v[114:115], v[14:15], v[10:11] op_sel_hi:[1,0,1]
	v_pk_fma_f32 v[12:13], v[116:117], v[14:15], v[12:13] op_sel_hi:[1,0,1]
	v_pk_fma_f32 v[6:7], v[114:115], v[14:15], v[6:7] op_sel:[0,1,0]
	v_pk_fma_f32 v[8:9], v[116:117], v[14:15], v[8:9] op_sel:[0,1,0]
	v_pk_fma_f32 v[2:3], v[114:115], v[16:17], v[2:3] op_sel_hi:[1,0,1]
	v_pk_fma_f32 v[4:5], v[116:117], v[16:17], v[4:5] op_sel_hi:[1,0,1]
	v_pk_fma_f32 v[14:15], v[114:115], v[170:171], v[18:19] op_sel_hi:[1,0,1]
	v_pk_fma_f32 v[16:17], v[116:117], v[170:171], v[20:21] op_sel_hi:[1,0,1]
	v_addc_co_u32_e32 v199, vcc, 0, v197, vcc
	global_load_dwordx4 v[114:117], v[198:199], off
	v_add_co_u32_e32 v198, vcc, s13, v196
	s_waitcnt vmcnt(15)
	v_pk_fma_f32 v[10:11], v[118:119], v[30:31], v[10:11] op_sel_hi:[1,0,1]
	v_pk_fma_f32 v[12:13], v[120:121], v[30:31], v[12:13] op_sel_hi:[1,0,1]
	v_pk_fma_f32 v[6:7], v[118:119], v[30:31], v[6:7] op_sel:[0,1,0]
	v_pk_fma_f32 v[8:9], v[120:121], v[30:31], v[8:9] op_sel:[0,1,0]
	v_pk_fma_f32 v[2:3], v[118:119], v[32:33], v[2:3] op_sel_hi:[1,0,1]
	v_pk_fma_f32 v[4:5], v[120:121], v[32:33], v[4:5] op_sel_hi:[1,0,1]
	v_pk_fma_f32 v[14:15], v[118:119], v[172:173], v[14:15] op_sel_hi:[1,0,1]
	v_pk_fma_f32 v[16:17], v[120:121], v[172:173], v[16:17] op_sel_hi:[1,0,1]
	v_addc_co_u32_e32 v199, vcc, 0, v197, vcc
	global_load_dwordx4 v[118:121], v[198:199], off
	v_add_co_u32_e32 v198, vcc, s14, v196
	s_waitcnt vmcnt(15)
	v_pk_fma_f32 v[10:11], v[122:123], v[34:35], v[10:11] op_sel_hi:[1,0,1]
	v_pk_fma_f32 v[12:13], v[124:125], v[34:35], v[12:13] op_sel_hi:[1,0,1]
	v_pk_fma_f32 v[6:7], v[122:123], v[34:35], v[6:7] op_sel:[0,1,0]
	v_pk_fma_f32 v[8:9], v[124:125], v[34:35], v[8:9] op_sel:[0,1,0]
	v_pk_fma_f32 v[2:3], v[122:123], v[36:37], v[2:3] op_sel_hi:[1,0,1]
	v_pk_fma_f32 v[4:5], v[124:125], v[36:37], v[4:5] op_sel_hi:[1,0,1]
	v_pk_fma_f32 v[14:15], v[122:123], v[174:175], v[14:15] op_sel_hi:[1,0,1]
	v_pk_fma_f32 v[16:17], v[124:125], v[174:175], v[16:17] op_sel_hi:[1,0,1]
	v_addc_co_u32_e32 v199, vcc, 0, v197, vcc
	global_load_dwordx4 v[122:125], v[198:199], off
	v_add_co_u32_e32 v198, vcc, s15, v196
	s_waitcnt vmcnt(15)
	v_pk_fma_f32 v[10:11], v[126:127], v[38:39], v[10:11] op_sel_hi:[1,0,1]
	v_pk_fma_f32 v[12:13], v[128:129], v[38:39], v[12:13] op_sel_hi:[1,0,1]
	v_pk_fma_f32 v[6:7], v[126:127], v[38:39], v[6:7] op_sel:[0,1,0]
	v_pk_fma_f32 v[8:9], v[128:129], v[38:39], v[8:9] op_sel:[0,1,0]
	v_pk_fma_f32 v[2:3], v[126:127], v[40:41], v[2:3] op_sel_hi:[1,0,1]
	v_pk_fma_f32 v[4:5], v[128:129], v[40:41], v[4:5] op_sel_hi:[1,0,1]
	v_pk_fma_f32 v[14:15], v[126:127], v[176:177], v[14:15] op_sel_hi:[1,0,1]
	v_pk_fma_f32 v[16:17], v[128:129], v[176:177], v[16:17] op_sel_hi:[1,0,1]
	v_addc_co_u32_e32 v199, vcc, 0, v197, vcc
	global_load_dwordx4 v[126:129], v[198:199], off
	v_add_co_u32_e32 v198, vcc, s16, v196
	s_waitcnt vmcnt(15)
	v_pk_fma_f32 v[10:11], v[130:131], v[42:43], v[10:11] op_sel_hi:[1,0,1]
	v_pk_fma_f32 v[12:13], v[132:133], v[42:43], v[12:13] op_sel_hi:[1,0,1]
	v_pk_fma_f32 v[6:7], v[130:131], v[42:43], v[6:7] op_sel:[0,1,0]
	v_pk_fma_f32 v[8:9], v[132:133], v[42:43], v[8:9] op_sel:[0,1,0]
	v_pk_fma_f32 v[2:3], v[130:131], v[44:45], v[2:3] op_sel_hi:[1,0,1]
	v_pk_fma_f32 v[4:5], v[132:133], v[44:45], v[4:5] op_sel_hi:[1,0,1]
	v_pk_fma_f32 v[14:15], v[130:131], v[178:179], v[14:15] op_sel_hi:[1,0,1]
	v_pk_fma_f32 v[16:17], v[132:133], v[178:179], v[16:17] op_sel_hi:[1,0,1]
	v_addc_co_u32_e32 v199, vcc, 0, v197, vcc
	global_load_dwordx4 v[130:133], v[198:199], off
	v_add_co_u32_e32 v198, vcc, s17, v196
	s_waitcnt vmcnt(15)
	v_pk_fma_f32 v[10:11], v[134:135], v[46:47], v[10:11] op_sel_hi:[1,0,1]
	v_pk_fma_f32 v[12:13], v[136:137], v[46:47], v[12:13] op_sel_hi:[1,0,1]
	v_pk_fma_f32 v[6:7], v[134:135], v[46:47], v[6:7] op_sel:[0,1,0]
	v_pk_fma_f32 v[8:9], v[136:137], v[46:47], v[8:9] op_sel:[0,1,0]
	v_pk_fma_f32 v[2:3], v[134:135], v[48:49], v[2:3] op_sel_hi:[1,0,1]
	v_pk_fma_f32 v[4:5], v[136:137], v[48:49], v[4:5] op_sel_hi:[1,0,1]
	v_pk_fma_f32 v[14:15], v[134:135], v[180:181], v[14:15] op_sel_hi:[1,0,1]
	v_pk_fma_f32 v[16:17], v[136:137], v[180:181], v[16:17] op_sel_hi:[1,0,1]
	v_addc_co_u32_e32 v199, vcc, 0, v197, vcc
	global_load_dwordx4 v[134:137], v[198:199], off
	v_add_co_u32_e32 v198, vcc, s20, v196
	s_waitcnt vmcnt(15)
	v_pk_fma_f32 v[10:11], v[138:139], v[50:51], v[10:11] op_sel_hi:[1,0,1]
	v_pk_fma_f32 v[12:13], v[140:141], v[50:51], v[12:13] op_sel_hi:[1,0,1]
	v_pk_fma_f32 v[6:7], v[138:139], v[50:51], v[6:7] op_sel:[0,1,0]
	v_pk_fma_f32 v[8:9], v[140:141], v[50:51], v[8:9] op_sel:[0,1,0]
	v_pk_fma_f32 v[2:3], v[138:139], v[52:53], v[2:3] op_sel_hi:[1,0,1]
	v_pk_fma_f32 v[4:5], v[140:141], v[52:53], v[4:5] op_sel_hi:[1,0,1]
	v_pk_fma_f32 v[14:15], v[138:139], v[182:183], v[14:15] op_sel_hi:[1,0,1]
	v_pk_fma_f32 v[16:17], v[140:141], v[182:183], v[16:17] op_sel_hi:[1,0,1]
	v_addc_co_u32_e32 v199, vcc, 0, v197, vcc
	global_load_dwordx4 v[138:141], v[198:199], off
	v_add_co_u32_e32 v198, vcc, s21, v196
	s_waitcnt vmcnt(15)
	v_pk_fma_f32 v[10:11], v[142:143], v[78:79], v[10:11] op_sel_hi:[1,0,1]
	v_pk_fma_f32 v[12:13], v[144:145], v[78:79], v[12:13] op_sel_hi:[1,0,1]
	v_pk_fma_f32 v[6:7], v[142:143], v[78:79], v[6:7] op_sel:[0,1,0]
	v_pk_fma_f32 v[8:9], v[144:145], v[78:79], v[8:9] op_sel:[0,1,0]
	v_pk_fma_f32 v[2:3], v[142:143], v[80:81], v[2:3] op_sel_hi:[1,0,1]
	v_pk_fma_f32 v[4:5], v[144:145], v[80:81], v[4:5] op_sel_hi:[1,0,1]
	v_pk_fma_f32 v[14:15], v[142:143], v[184:185], v[14:15] op_sel_hi:[1,0,1]
	v_pk_fma_f32 v[16:17], v[144:145], v[184:185], v[16:17] op_sel_hi:[1,0,1]
	v_addc_co_u32_e32 v199, vcc, 0, v197, vcc
	global_load_dwordx4 v[142:145], v[198:199], off
	v_add_co_u32_e32 v198, vcc, s22, v196
	s_waitcnt vmcnt(15)
	v_pk_fma_f32 v[10:11], v[146:147], v[82:83], v[10:11] op_sel_hi:[1,0,1]
	v_pk_fma_f32 v[12:13], v[148:149], v[82:83], v[12:13] op_sel_hi:[1,0,1]
	v_pk_fma_f32 v[6:7], v[146:147], v[82:83], v[6:7] op_sel:[0,1,0]
	v_pk_fma_f32 v[8:9], v[148:149], v[82:83], v[8:9] op_sel:[0,1,0]
	v_pk_fma_f32 v[2:3], v[146:147], v[84:85], v[2:3] op_sel_hi:[1,0,1]
	v_pk_fma_f32 v[4:5], v[148:149], v[84:85], v[4:5] op_sel_hi:[1,0,1]
	v_pk_fma_f32 v[14:15], v[146:147], v[186:187], v[14:15] op_sel_hi:[1,0,1]
	v_pk_fma_f32 v[16:17], v[148:149], v[186:187], v[16:17] op_sel_hi:[1,0,1]
	v_addc_co_u32_e32 v199, vcc, 0, v197, vcc
	global_load_dwordx4 v[146:149], v[198:199], off
	v_add_co_u32_e32 v198, vcc, s23, v196
	s_waitcnt vmcnt(15)
	v_pk_fma_f32 v[10:11], v[150:151], v[86:87], v[10:11] op_sel_hi:[1,0,1]
	v_pk_fma_f32 v[12:13], v[152:153], v[86:87], v[12:13] op_sel_hi:[1,0,1]
	v_pk_fma_f32 v[6:7], v[150:151], v[86:87], v[6:7] op_sel:[0,1,0]
	v_pk_fma_f32 v[8:9], v[152:153], v[86:87], v[8:9] op_sel:[0,1,0]
	v_pk_fma_f32 v[2:3], v[150:151], v[88:89], v[2:3] op_sel_hi:[1,0,1]
	v_pk_fma_f32 v[4:5], v[152:153], v[88:89], v[4:5] op_sel_hi:[1,0,1]
	v_pk_fma_f32 v[14:15], v[150:151], v[188:189], v[14:15] op_sel_hi:[1,0,1]
	v_pk_fma_f32 v[16:17], v[152:153], v[188:189], v[16:17] op_sel_hi:[1,0,1]
	v_addc_co_u32_e32 v199, vcc, 0, v197, vcc
	global_load_dwordx4 v[150:153], v[198:199], off
	v_add_co_u32_e32 v198, vcc, s24, v196
	s_waitcnt vmcnt(15)
	v_pk_fma_f32 v[10:11], v[154:155], v[90:91], v[10:11] op_sel_hi:[1,0,1]
	v_pk_fma_f32 v[12:13], v[156:157], v[90:91], v[12:13] op_sel_hi:[1,0,1]
	v_pk_fma_f32 v[6:7], v[154:155], v[90:91], v[6:7] op_sel:[0,1,0]
	v_pk_fma_f32 v[8:9], v[156:157], v[90:91], v[8:9] op_sel:[0,1,0]
	v_pk_fma_f32 v[2:3], v[154:155], v[92:93], v[2:3] op_sel_hi:[1,0,1]
	v_pk_fma_f32 v[4:5], v[156:157], v[92:93], v[4:5] op_sel_hi:[1,0,1]
	v_pk_fma_f32 v[14:15], v[154:155], v[190:191], v[14:15] op_sel_hi:[1,0,1]
	v_pk_fma_f32 v[16:17], v[156:157], v[190:191], v[16:17] op_sel_hi:[1,0,1]
	v_addc_co_u32_e32 v199, vcc, 0, v197, vcc
	global_load_dwordx4 v[154:157], v[198:199], off
	v_add_co_u32_e32 v198, vcc, s25, v196
	s_waitcnt vmcnt(15)
	v_pk_fma_f32 v[10:11], v[158:159], v[94:95], v[10:11] op_sel_hi:[1,0,1]
	v_pk_fma_f32 v[12:13], v[160:161], v[94:95], v[12:13] op_sel_hi:[1,0,1]
	v_pk_fma_f32 v[6:7], v[158:159], v[94:95], v[6:7] op_sel:[0,1,0]
	v_pk_fma_f32 v[8:9], v[160:161], v[94:95], v[8:9] op_sel:[0,1,0]
	v_pk_fma_f32 v[2:3], v[158:159], v[96:97], v[2:3] op_sel_hi:[1,0,1]
	v_pk_fma_f32 v[4:5], v[160:161], v[96:97], v[4:5] op_sel_hi:[1,0,1]
	v_pk_fma_f32 v[14:15], v[158:159], v[192:193], v[14:15] op_sel_hi:[1,0,1]
	v_pk_fma_f32 v[16:17], v[160:161], v[192:193], v[16:17] op_sel_hi:[1,0,1]
	v_addc_co_u32_e32 v199, vcc, 0, v197, vcc
	global_load_dwordx4 v[158:161], v[198:199], off
	v_add_co_u32_e32 v198, vcc, s28, v196
	s_waitcnt vmcnt(15)
	v_pk_fma_f32 v[10:11], v[162:163], v[98:99], v[10:11] op_sel_hi:[1,0,1]
	v_pk_fma_f32 v[12:13], v[164:165], v[98:99], v[12:13] op_sel_hi:[1,0,1]
	v_pk_fma_f32 v[6:7], v[162:163], v[98:99], v[6:7] op_sel:[0,1,0]
	v_pk_fma_f32 v[8:9], v[164:165], v[98:99], v[8:9] op_sel:[0,1,0]
	v_pk_fma_f32 v[2:3], v[162:163], v[100:101], v[2:3] op_sel_hi:[1,0,1]
	v_pk_fma_f32 v[4:5], v[164:165], v[100:101], v[4:5] op_sel_hi:[1,0,1]
	v_pk_fma_f32 v[62:63], v[162:163], v[194:195], v[14:15] op_sel_hi:[1,0,1]
	v_pk_fma_f32 v[60:61], v[164:165], v[194:195], v[16:17] op_sel_hi:[1,0,1]
	v_addc_co_u32_e32 v199, vcc, 0, v197, vcc
	global_load_dwordx4 v[162:165], v[198:199], off
	s_cmp_eq_u32 s4, 0x480000
	s_cbranch_scc0 .Lq_p0_loop
	ds_read_b128 v[26:29], v54
	ds_read_b128 v[22:25], v54 offset:16
	ds_read_b128 v[18:21], v54 offset:32
	ds_read_b128 v[14:17], v54 offset:48
	ds_read_b128 v[30:33], v54 offset:64
	ds_read_b128 v[34:37], v54 offset:80
	ds_read_b128 v[38:41], v54 offset:96
	ds_read_b128 v[42:45], v54 offset:112
	ds_read_b128 v[46:49], v54 offset:128
	ds_read_b128 v[50:53], v54 offset:144
	ds_read_b128 v[78:81], v54 offset:160
	ds_read_b128 v[82:85], v54 offset:176
	ds_read_b128 v[86:89], v54 offset:192
	ds_read_b128 v[90:93], v54 offset:208
	ds_read_b128 v[94:97], v54 offset:224
	ds_read_b128 v[98:101], v54 offset:240
	s_waitcnt lgkmcnt(0)
	v_mov_b32_e32 v166, v25
	v_mov_b32_e32 v168, v21
	v_mov_b32_e32 v170, v17
	v_mov_b32_e32 v172, v33
	v_mov_b32_e32 v174, v37
	v_mov_b32_e32 v176, v41
	v_mov_b32_e32 v178, v45
	v_mov_b32_e32 v180, v49
	v_mov_b32_e32 v182, v53
	v_mov_b32_e32 v184, v81
	v_mov_b32_e32 v186, v85
	v_mov_b32_e32 v188, v89
	v_mov_b32_e32 v190, v93
	v_mov_b32_e32 v64, v29
	v_mov_b32_e32 v192, v97
	v_mov_b32_e32 v194, v101
	v_add_u32_e32 v54, 0x100, v54
	s_waitcnt vmcnt(15)
	v_pk_fma_f32 v[10:11], v[102:103], v[26:27], v[10:11] op_sel_hi:[1,0,1]
	v_pk_fma_f32 v[12:13], v[104:105], v[26:27], v[12:13] op_sel_hi:[1,0,1]
	v_pk_fma_f32 v[6:7], v[102:103], v[26:27], v[6:7] op_sel:[0,1,0]
	v_pk_fma_f32 v[8:9], v[104:105], v[26:27], v[8:9] op_sel:[0,1,0]
	v_pk_fma_f32 v[2:3], v[102:103], v[28:29], v[2:3] op_sel_hi:[1,0,1]
	v_pk_fma_f32 v[4:5], v[104:105], v[28:29], v[4:5] op_sel_hi:[1,0,1]
	v_pk_fma_f32 v[26:27], v[102:103], v[64:65], v[62:63] op_sel_hi:[1,0,1]
	v_pk_fma_f32 v[28:29], v[104:105], v[64:65], v[60:61] op_sel_hi:[1,0,1]
	s_waitcnt vmcnt(14)
	v_pk_fma_f32 v[10:11], v[106:107], v[22:23], v[10:11] op_sel_hi:[1,0,1]
	v_pk_fma_f32 v[12:13], v[108:109], v[22:23], v[12:13] op_sel_hi:[1,0,1]
	v_pk_fma_f32 v[6:7], v[106:107], v[22:23], v[6:7] op_sel:[0,1,0]
	v_pk_fma_f32 v[8:9], v[108:109], v[22:23], v[8:9] op_sel:[0,1,0]
	v_pk_fma_f32 v[2:3], v[106:107], v[24:25], v[2:3] op_sel_hi:[1,0,1]
	v_pk_fma_f32 v[4:5], v[108:109], v[24:25], v[4:5] op_sel_hi:[1,0,1]
	v_pk_fma_f32 v[22:23], v[106:107], v[166:167], v[26:27] op_sel_hi:[1,0,1]
	v_pk_fma_f32 v[24:25], v[108:109], v[166:167], v[28:29] op_sel_hi:[1,0,1]
	s_waitcnt vmcnt(13)
	v_pk_fma_f32 v[10:11], v[110:111], v[18:19], v[10:11] op_sel_hi:[1,0,1]
	v_pk_fma_f32 v[12:13], v[112:113], v[18:19], v[12:13] op_sel_hi:[1,0,1]
	v_pk_fma_f32 v[6:7], v[110:111], v[18:19], v[6:7] op_sel:[0,1,0]
	v_pk_fma_f32 v[8:9], v[112:113], v[18:19], v[8:9] op_sel:[0,1,0]
	v_pk_fma_f32 v[2:3], v[110:111], v[20:21], v[2:3] op_sel_hi:[1,0,1]
	v_pk_fma_f32 v[4:5], v[112:113], v[20:21], v[4:5] op_sel_hi:[1,0,1]
	v_pk_fma_f32 v[18:19], v[110:111], v[168:169], v[22:23] op_sel_hi:[1,0,1]
	v_pk_fma_f32 v[20:21], v[112:113], v[168:169], v[24:25] op_sel_hi:[1,0,1]
	s_waitcnt vmcnt(12)
	v_pk_fma_f32 v[10:11], v[114:115], v[14:15], v[10:11] op_sel_hi:[1,0,1]
	v_pk_fma_f32 v[12:13], v[116:117], v[14:15], v[12:13] op_sel_hi:[1,0,1]
	v_pk_fma_f32 v[6:7], v[114:115], v[14:15], v[6:7] op_sel:[0,1,0]
	v_pk_fma_f32 v[8:9], v[116:117], v[14:15], v[8:9] op_sel:[0,1,0]
	v_pk_fma_f32 v[2:3], v[114:115], v[16:17], v[2:3] op_sel_hi:[1,0,1]
	v_pk_fma_f32 v[4:5], v[116:117], v[16:17], v[4:5] op_sel_hi:[1,0,1]
	v_pk_fma_f32 v[14:15], v[114:115], v[170:171], v[18:19] op_sel_hi:[1,0,1]
	v_pk_fma_f32 v[16:17], v[116:117], v[170:171], v[20:21] op_sel_hi:[1,0,1]
	s_waitcnt vmcnt(11)
	v_pk_fma_f32 v[10:11], v[118:119], v[30:31], v[10:11] op_sel_hi:[1,0,1]
	v_pk_fma_f32 v[12:13], v[120:121], v[30:31], v[12:13] op_sel_hi:[1,0,1]
	v_pk_fma_f32 v[6:7], v[118:119], v[30:31], v[6:7] op_sel:[0,1,0]
	v_pk_fma_f32 v[8:9], v[120:121], v[30:31], v[8:9] op_sel:[0,1,0]
	v_pk_fma_f32 v[2:3], v[118:119], v[32:33], v[2:3] op_sel_hi:[1,0,1]
	v_pk_fma_f32 v[4:5], v[120:121], v[32:33], v[4:5] op_sel_hi:[1,0,1]
	v_pk_fma_f32 v[14:15], v[118:119], v[172:173], v[14:15] op_sel_hi:[1,0,1]
	v_pk_fma_f32 v[16:17], v[120:121], v[172:173], v[16:17] op_sel_hi:[1,0,1]
	s_waitcnt vmcnt(10)
	v_pk_fma_f32 v[10:11], v[122:123], v[34:35], v[10:11] op_sel_hi:[1,0,1]
	v_pk_fma_f32 v[12:13], v[124:125], v[34:35], v[12:13] op_sel_hi:[1,0,1]
	v_pk_fma_f32 v[6:7], v[122:123], v[34:35], v[6:7] op_sel:[0,1,0]
	v_pk_fma_f32 v[8:9], v[124:125], v[34:35], v[8:9] op_sel:[0,1,0]
	v_pk_fma_f32 v[2:3], v[122:123], v[36:37], v[2:3] op_sel_hi:[1,0,1]
	v_pk_fma_f32 v[4:5], v[124:125], v[36:37], v[4:5] op_sel_hi:[1,0,1]
	v_pk_fma_f32 v[14:15], v[122:123], v[174:175], v[14:15] op_sel_hi:[1,0,1]
	v_pk_fma_f32 v[16:17], v[124:125], v[174:175], v[16:17] op_sel_hi:[1,0,1]
	s_waitcnt vmcnt(9)
	v_pk_fma_f32 v[10:11], v[126:127], v[38:39], v[10:11] op_sel_hi:[1,0,1]
	v_pk_fma_f32 v[12:13], v[128:129], v[38:39], v[12:13] op_sel_hi:[1,0,1]
	v_pk_fma_f32 v[6:7], v[126:127], v[38:39], v[6:7] op_sel:[0,1,0]
	v_pk_fma_f32 v[8:9], v[128:129], v[38:39], v[8:9] op_sel:[0,1,0]
	v_pk_fma_f32 v[2:3], v[126:127], v[40:41], v[2:3] op_sel_hi:[1,0,1]
	v_pk_fma_f32 v[4:5], v[128:129], v[40:41], v[4:5] op_sel_hi:[1,0,1]
	v_pk_fma_f32 v[14:15], v[126:127], v[176:177], v[14:15] op_sel_hi:[1,0,1]
	v_pk_fma_f32 v[16:17], v[128:129], v[176:177], v[16:17] op_sel_hi:[1,0,1]
	s_waitcnt vmcnt(8)
	v_pk_fma_f32 v[10:11], v[130:131], v[42:43], v[10:11] op_sel_hi:[1,0,1]
	v_pk_fma_f32 v[12:13], v[132:133], v[42:43], v[12:13] op_sel_hi:[1,0,1]
	v_pk_fma_f32 v[6:7], v[130:131], v[42:43], v[6:7] op_sel:[0,1,0]
	v_pk_fma_f32 v[8:9], v[132:133], v[42:43], v[8:9] op_sel:[0,1,0]
	v_pk_fma_f32 v[2:3], v[130:131], v[44:45], v[2:3] op_sel_hi:[1,0,1]
	v_pk_fma_f32 v[4:5], v[132:133], v[44:45], v[4:5] op_sel_hi:[1,0,1]
	v_pk_fma_f32 v[14:15], v[130:131], v[178:179], v[14:15] op_sel_hi:[1,0,1]
	v_pk_fma_f32 v[16:17], v[132:133], v[178:179], v[16:17] op_sel_hi:[1,0,1]
	s_waitcnt vmcnt(7)
	v_pk_fma_f32 v[10:11], v[134:135], v[46:47], v[10:11] op_sel_hi:[1,0,1]
	v_pk_fma_f32 v[12:13], v[136:137], v[46:47], v[12:13] op_sel_hi:[1,0,1]
	v_pk_fma_f32 v[6:7], v[134:135], v[46:47], v[6:7] op_sel:[0,1,0]
	v_pk_fma_f32 v[8:9], v[136:137], v[46:47], v[8:9] op_sel:[0,1,0]
	v_pk_fma_f32 v[2:3], v[134:135], v[48:49], v[2:3] op_sel_hi:[1,0,1]
	v_pk_fma_f32 v[4:5], v[136:137], v[48:49], v[4:5] op_sel_hi:[1,0,1]
	v_pk_fma_f32 v[14:15], v[134:135], v[180:181], v[14:15] op_sel_hi:[1,0,1]
	v_pk_fma_f32 v[16:17], v[136:137], v[180:181], v[16:17] op_sel_hi:[1,0,1]
	s_waitcnt vmcnt(6)
	v_pk_fma_f32 v[10:11], v[138:139], v[50:51], v[10:11] op_sel_hi:[1,0,1]
	v_pk_fma_f32 v[12:13], v[140:141], v[50:51], v[12:13] op_sel_hi:[1,0,1]
	v_pk_fma_f32 v[6:7], v[138:139], v[50:51], v[6:7] op_sel:[0,1,0]
	v_pk_fma_f32 v[8:9], v[140:141], v[50:51], v[8:9] op_sel:[0,1,0]
	v_pk_fma_f32 v[2:3], v[138:139], v[52:53], v[2:3] op_sel_hi:[1,0,1]
	v_pk_fma_f32 v[4:5], v[140:141], v[52:53], v[4:5] op_sel_hi:[1,0,1]
	v_pk_fma_f32 v[14:15], v[138:139], v[182:183], v[14:15] op_sel_hi:[1,0,1]
	v_pk_fma_f32 v[16:17], v[140:141], v[182:183], v[16:17] op_sel_hi:[1,0,1]
	s_waitcnt vmcnt(5)
	v_pk_fma_f32 v[10:11], v[142:143], v[78:79], v[10:11] op_sel_hi:[1,0,1]
	v_pk_fma_f32 v[12:13], v[144:145], v[78:79], v[12:13] op_sel_hi:[1,0,1]
	v_pk_fma_f32 v[6:7], v[142:143], v[78:79], v[6:7] op_sel:[0,1,0]
	v_pk_fma_f32 v[8:9], v[144:145], v[78:79], v[8:9] op_sel:[0,1,0]
	v_pk_fma_f32 v[2:3], v[142:143], v[80:81], v[2:3] op_sel_hi:[1,0,1]
	v_pk_fma_f32 v[4:5], v[144:145], v[80:81], v[4:5] op_sel_hi:[1,0,1]
	v_pk_fma_f32 v[14:15], v[142:143], v[184:185], v[14:15] op_sel_hi:[1,0,1]
	v_pk_fma_f32 v[16:17], v[144:145], v[184:185], v[16:17] op_sel_hi:[1,0,1]
	s_waitcnt vmcnt(4)
	v_pk_fma_f32 v[10:11], v[146:147], v[82:83], v[10:11] op_sel_hi:[1,0,1]
	v_pk_fma_f32 v[12:13], v[148:149], v[82:83], v[12:13] op_sel_hi:[1,0,1]
	v_pk_fma_f32 v[6:7], v[146:147], v[82:83], v[6:7] op_sel:[0,1,0]
	v_pk_fma_f32 v[8:9], v[148:149], v[82:83], v[8:9] op_sel:[0,1,0]
	v_pk_fma_f32 v[2:3], v[146:147], v[84:85], v[2:3] op_sel_hi:[1,0,1]
	v_pk_fma_f32 v[4:5], v[148:149], v[84:85], v[4:5] op_sel_hi:[1,0,1]
	v_pk_fma_f32 v[14:15], v[146:147], v[186:187], v[14:15] op_sel_hi:[1,0,1]
	v_pk_fma_f32 v[16:17], v[148:149], v[186:187], v[16:17] op_sel_hi:[1,0,1]
	s_waitcnt vmcnt(3)
	v_pk_fma_f32 v[10:11], v[150:151], v[86:87], v[10:11] op_sel_hi:[1,0,1]
	v_pk_fma_f32 v[12:13], v[152:153], v[86:87], v[12:13] op_sel_hi:[1,0,1]
	v_pk_fma_f32 v[6:7], v[150:151], v[86:87], v[6:7] op_sel:[0,1,0]
	v_pk_fma_f32 v[8:9], v[152:153], v[86:87], v[8:9] op_sel:[0,1,0]
	v_pk_fma_f32 v[2:3], v[150:151], v[88:89], v[2:3] op_sel_hi:[1,0,1]
	v_pk_fma_f32 v[4:5], v[152:153], v[88:89], v[4:5] op_sel_hi:[1,0,1]
	v_pk_fma_f32 v[14:15], v[150:151], v[188:189], v[14:15] op_sel_hi:[1,0,1]
	v_pk_fma_f32 v[16:17], v[152:153], v[188:189], v[16:17] op_sel_hi:[1,0,1]
	s_waitcnt vmcnt(2)
	v_pk_fma_f32 v[10:11], v[154:155], v[90:91], v[10:11] op_sel_hi:[1,0,1]
	v_pk_fma_f32 v[12:13], v[156:157], v[90:91], v[12:13] op_sel_hi:[1,0,1]
	v_pk_fma_f32 v[6:7], v[154:155], v[90:91], v[6:7] op_sel:[0,1,0]
	v_pk_fma_f32 v[8:9], v[156:157], v[90:91], v[8:9] op_sel:[0,1,0]
	v_pk_fma_f32 v[2:3], v[154:155], v[92:93], v[2:3] op_sel_hi:[1,0,1]
	v_pk_fma_f32 v[4:5], v[156:157], v[92:93], v[4:5] op_sel_hi:[1,0,1]
	v_pk_fma_f32 v[14:15], v[154:155], v[190:191], v[14:15] op_sel_hi:[1,0,1]
	v_pk_fma_f32 v[16:17], v[156:157], v[190:191], v[16:17] op_sel_hi:[1,0,1]
	s_waitcnt vmcnt(1)
	v_pk_fma_f32 v[10:11], v[158:159], v[94:95], v[10:11] op_sel_hi:[1,0,1]
	v_pk_fma_f32 v[12:13], v[160:161], v[94:95], v[12:13] op_sel_hi:[1,0,1]
	v_pk_fma_f32 v[6:7], v[158:159], v[94:95], v[6:7] op_sel:[0,1,0]
	v_pk_fma_f32 v[8:9], v[160:161], v[94:95], v[8:9] op_sel:[0,1,0]
	v_pk_fma_f32 v[2:3], v[158:159], v[96:97], v[2:3] op_sel_hi:[1,0,1]
	v_pk_fma_f32 v[4:5], v[160:161], v[96:97], v[4:5] op_sel_hi:[1,0,1]
	v_pk_fma_f32 v[14:15], v[158:159], v[192:193], v[14:15] op_sel_hi:[1,0,1]
	v_pk_fma_f32 v[16:17], v[160:161], v[192:193], v[16:17] op_sel_hi:[1,0,1]
	s_waitcnt vmcnt(0)
	v_pk_fma_f32 v[10:11], v[162:163], v[98:99], v[10:11] op_sel_hi:[1,0,1]
	v_pk_fma_f32 v[12:13], v[164:165], v[98:99], v[12:13] op_sel_hi:[1,0,1]
	v_pk_fma_f32 v[6:7], v[162:163], v[98:99], v[6:7] op_sel:[0,1,0]
	v_pk_fma_f32 v[8:9], v[164:165], v[98:99], v[8:9] op_sel:[0,1,0]
	v_pk_fma_f32 v[2:3], v[162:163], v[100:101], v[2:3] op_sel_hi:[1,0,1]
	v_pk_fma_f32 v[4:5], v[164:165], v[100:101], v[4:5] op_sel_hi:[1,0,1]
	v_pk_fma_f32 v[62:63], v[162:163], v[194:195], v[14:15] op_sel_hi:[1,0,1]
	v_pk_fma_f32 v[60:61], v[164:165], v[194:195], v[16:17] op_sel_hi:[1,0,1]
	s_add_i32 s1, s29, 0x5f
	ds_write_b128 v69, v[10:13]
	ds_write_b128 v69, v[6:9] offset:1024
	ds_write_b128 v69, v[2:5] offset:2048
	ds_write_b32 v70, v62
	ds_write_b32 v71, v63
	ds_write_b32 v72, v60
	ds_write_b32 v73, v61
	s_cmpk_lt_u32 s1, 0xbf
	v_or_b32_sdwa v2, s0, v0 dst_sel:DWORD dst_unused:UNUSED_PAD src0_sel:DWORD src1_sel:BYTE_0
	s_cselect_b64 s[4:5], -1, 0
	s_ashr_i32 s1, s0, 31
	v_ashrrev_i32_e32 v3, 31, v2
	v_lshl_add_u64 v[2:3], v[2:3], 2, s[58:59]
	v_lshl_add_u64 v[4:5], s[0:1], 2, v[56:57]
	s_mov_b64 s[0:1], 0
	v_mov_b32_e32 v6, v77
	v_mov_b32_e32 v7, v76
	v_mov_b32_e32 v8, v75
	s_waitcnt lgkmcnt(0)
	s_barrier
	s_branch .LBB8_16
